# low-rank rmsnorm pass rewritten by hand: 8 rows per step, their 16 wave sums reduced together with DPP row ops instead of 96 serial LDS shuffles
# speedup vs baseline: 1.0082x; 1.0082x over previous
; __device__ __forceinline__ const float* inp(int k) { const CAS cfptr* p = (const CAS cfptr*)__builtin_amdgcn_kernarg_segment_ptr(); asm volatile("" : "+s"(p)); return p[k]; }
; #define LANE_IDS() const int f_tid = tid_(); const int f_lane = f_tid & 63; const int f_gtid = blockIdx.x * (NWAVES * 64) + f_tid; (void)f_lane; (void)f_gtid
; #define IN(k) ((((PH_MASK) >> (k)) & 1u) && kargs()->ph_lo <= (k) && (k) < kargs()->ph_hi)
; #define SEAM(k) do { if (IN((k) + 1)) xcd_barrier(xbar); } while (0)
; #define PH_PTRS() unsigned char* ws = kargs()->ws; F.ws = ws; F.out = kargs()->out; float* mod = (float*)(ws + WS_MOD); const float* mod1 = mod + 9 * MODS; bf16* X = (bf16*)(ws + WS_X);     bf16* H = (bf16*)(ws + WS_H); (void)mod; (void)mod1; (void)X; (void)H
; __device__ __forceinline__ void p12_lrnorm(Frame& F, const Args& A) {
;     LANE_IDS();
;     unsigned char* ws = F.ws;
;     const bf16* PX = (const bf16*)(ws + WS_PX); bf16* QL = (bf16*)((unsigned char*)F.out + OUT_QL); bf16* CKV = (bf16*)(ws + WS_CKV); bf16* KPE = (bf16*)(ws + WS_KPE);
;     const float* gqa = inp(22); const float* gkva = inp(23);
;     constexpr int NR = 8;
;     for (int row0 = F.gw; row0 < NTOK; row0 += NR * F.NGW) {
;         bf16x8 qraw[NR]; u32x2 kraw[NR]; u32x4 praw[NR];
; #pragma unroll
;         for (int r = 0; r < NR; ++r) { const int row = row0 + r * F.NGW; if (row < NTOK) { const bf16* pr = PX + (size_t)row * DM;
;             if (row < NLAT) qraw[r] = *(const bf16x8*)(pr + 8 * f_lane);
;             kraw[r] = *(const u32x2*)(pr + QLR + 4 * f_lane);
;             if (f_lane < 4) praw[r] = *(const u32x4*)(pr + QLR + KVLR + 8 * f_lane); } }
; __global__ void __launch_bounds__(NWAVES * 64, 2) mk_fwd(Args args) {
;     ...
;     if (IN(13)) for (int rep_ = 0; rep_ < PH_REPS(13); ++rep_) { PH_PTRS(); p12_lrnorm(F, args); if (rep_ == PH_REPS(13) - 1) SEAM(13); }
.LBB0_1298:
	s_mov_b64 s[4:5], s[0:1]
	s_load_dword s3, s[4:5], 0xf8
	s_waitcnt lgkmcnt(0)
	s_cmp_gt_i32 s3, 13
	s_cbranch_scc1 .LBB0_1466
	s_mov_b64 s[4:5], s[0:1]
	s_load_dword s3, s[4:5], 0xfc
	s_waitcnt lgkmcnt(0)
	s_cmp_lt_i32 s3, 14
	s_cbranch_scc1 .LBB0_1466
	s_cmp_gt_i32 s46, 0x87ff
	s_mov_b64 s[6:7], s[0:1]
	s_mov_b64 s[4:5], s[0:1]
	v_mov_b32_e32 v0, v188
	s_mov_b64 s[10:11], s[0:1]
	s_mov_b64 s[12:13], s[0:1]
	s_cbranch_scc1 .LBB0_1411
	s_load_dwordx2 s[14:15], s[0:1], 0xf0
	s_load_dwordx2 s[16:17], s[0:1], 0xe8
	s_load_dwordx2 s[18:19], s[0:1], 0xb0
	s_load_dwordx2 s[20:21], s[0:1], 0xb8
	v_and_b32_e32 v2, 63, v188
	v_lshlrev_b32_e32 v3, 4, v2
	v_lshlrev_b32_e32 v4, 3, v2
	v_lshlrev_b32_e32 v5, 5, v2
	s_waitcnt lgkmcnt(0)
	global_load_dwordx4 v[8:11], v5, s[18:19]
	global_load_dwordx4 v[12:15], v5, s[18:19] offset:16
	global_load_dwordx4 v[16:19], v3, s[20:21]
	s_add_u32 s4, s14, 0x12c00000
	s_addc_u32 s5, s15, 0
	s_add_u32 s6, s16, 0x6000000
	s_addc_u32 s7, s17, 0
	s_add_u32 s8, s14, 0x900000
	s_addc_u32 s9, s15, 0
	s_add_u32 s10, s14, 0x600000
	s_addc_u32 s11, s15, 0
	s_mov_b32 s12, 0
.Llr_step:
	s_add_i32 s13, s12, 0
	s_mul_i32 s13, s13, s76
	s_add_i32 s34, s13, s46
	s_min_i32 s22, s34, 0x87ff
	s_add_i32 s13, s12, 1
	s_mul_i32 s13, s13, s76
	s_add_i32 s35, s13, s46
	s_min_i32 s23, s35, 0x87ff
	s_add_i32 s13, s12, 2
	s_mul_i32 s13, s13, s76
	s_add_i32 s36, s13, s46
	s_min_i32 s24, s36, 0x87ff
	s_add_i32 s13, s12, 3
	s_mul_i32 s13, s13, s76
	s_add_i32 s37, s13, s46
	s_min_i32 s25, s37, 0x87ff
	s_add_i32 s13, s12, 4
	s_mul_i32 s13, s13, s76
	s_add_i32 s38, s13, s46
	s_min_i32 s26, s38, 0x87ff
	s_add_i32 s13, s12, 5
	s_mul_i32 s13, s13, s76
	s_add_i32 s39, s13, s46
	s_min_i32 s27, s39, 0x87ff
	s_add_i32 s13, s12, 6
	s_mul_i32 s13, s13, s76
	s_add_i32 s40, s13, s46
	s_min_i32 s28, s40, 0x87ff
	s_add_i32 s13, s12, 7
	s_mul_i32 s13, s13, s76
	s_add_i32 s41, s13, s46
	s_min_i32 s29, s41, 0x87ff
	s_lshl_b32 s13, s22, 11
	s_add_u32 s30, s4, s13
	s_addc_u32 s31, s5, 0
	global_load_dwordx4 v[32:35], v3, s[30:31]
	global_load_dwordx2 v[64:65], v4, s[30:31] offset:1024
	s_mov_b64 exec, 15
	global_load_dwordx4 v[80:83], v3, s[30:31] offset:1536
	s_mov_b64 exec, -1
	s_lshl_b32 s13, s23, 11
	s_add_u32 s30, s4, s13
	s_addc_u32 s31, s5, 0
	global_load_dwordx4 v[36:39], v3, s[30:31]
	global_load_dwordx2 v[66:67], v4, s[30:31] offset:1024
	s_mov_b64 exec, 15
	global_load_dwordx4 v[84:87], v3, s[30:31] offset:1536
	s_mov_b64 exec, -1
	s_lshl_b32 s13, s24, 11
	s_add_u32 s30, s4, s13
	s_addc_u32 s31, s5, 0
	global_load_dwordx4 v[40:43], v3, s[30:31]
	global_load_dwordx2 v[68:69], v4, s[30:31] offset:1024
	s_mov_b64 exec, 15
	global_load_dwordx4 v[88:91], v3, s[30:31] offset:1536
	s_mov_b64 exec, -1
	s_lshl_b32 s13, s25, 11
	s_add_u32 s30, s4, s13
	s_addc_u32 s31, s5, 0
	global_load_dwordx4 v[44:47], v3, s[30:31]
	global_load_dwordx2 v[70:71], v4, s[30:31] offset:1024
	s_mov_b64 exec, 15
	global_load_dwordx4 v[92:95], v3, s[30:31] offset:1536
	s_mov_b64 exec, -1
	s_lshl_b32 s13, s26, 11
	s_add_u32 s30, s4, s13
	s_addc_u32 s31, s5, 0
	global_load_dwordx4 v[48:51], v3, s[30:31]
	global_load_dwordx2 v[72:73], v4, s[30:31] offset:1024
	s_mov_b64 exec, 15
	global_load_dwordx4 v[96:99], v3, s[30:31] offset:1536
	s_mov_b64 exec, -1
	s_lshl_b32 s13, s27, 11
	s_add_u32 s30, s4, s13
	s_addc_u32 s31, s5, 0
	global_load_dwordx4 v[52:55], v3, s[30:31]
	global_load_dwordx2 v[74:75], v4, s[30:31] offset:1024
	s_mov_b64 exec, 15
	global_load_dwordx4 v[100:103], v3, s[30:31] offset:1536
	s_mov_b64 exec, -1
	s_lshl_b32 s13, s28, 11
	s_add_u32 s30, s4, s13
	s_addc_u32 s31, s5, 0
	global_load_dwordx4 v[56:59], v3, s[30:31]
	global_load_dwordx2 v[76:77], v4, s[30:31] offset:1024
	s_mov_b64 exec, 15
	global_load_dwordx4 v[104:107], v3, s[30:31] offset:1536
	s_mov_b64 exec, -1
	s_lshl_b32 s13, s29, 11
	s_add_u32 s30, s4, s13
	s_addc_u32 s31, s5, 0
	global_load_dwordx4 v[60:63], v3, s[30:31]
	global_load_dwordx2 v[78:79], v4, s[30:31] offset:1024
	s_mov_b64 exec, 15
	global_load_dwordx4 v[108:111], v3, s[30:31] offset:1536
	s_mov_b64 exec, -1
	s_waitcnt vmcnt(0)
	v_lshlrev_b32_e32 v120, 16, v32
	v_and_b32_e32 v121, 0xffff0000, v32
	v_lshlrev_b32_e32 v122, 16, v33
	v_and_b32_e32 v123, 0xffff0000, v33
	v_lshlrev_b32_e32 v124, 16, v34
	v_and_b32_e32 v125, 0xffff0000, v34
	v_lshlrev_b32_e32 v126, 16, v35
	v_and_b32_e32 v7, 0xffff0000, v35
	v_mul_f32_e32 v20, v120, v120
	v_fmac_f32_e32 v20, v121, v121
	v_fmac_f32_e32 v20, v122, v122
	v_fmac_f32_e32 v20, v123, v123
	v_fmac_f32_e32 v20, v124, v124
	v_fmac_f32_e32 v20, v125, v125
	v_fmac_f32_e32 v20, v126, v126
	v_fmac_f32_e32 v20, v7, v7
	v_lshlrev_b32_e32 v120, 16, v64
	v_and_b32_e32 v121, 0xffff0000, v64
	v_lshlrev_b32_e32 v122, 16, v65
	v_and_b32_e32 v123, 0xffff0000, v65
	v_mul_f32_e32 v112, v120, v120
	v_fmac_f32_e32 v112, v121, v121
	v_mul_f32_e32 v124, v122, v122
	v_fmac_f32_e32 v124, v123, v123
	v_add_f32_e32 v112, v112, v124
	v_lshlrev_b32_e32 v120, 16, v36
	v_and_b32_e32 v121, 0xffff0000, v36
	v_lshlrev_b32_e32 v122, 16, v37
	v_and_b32_e32 v123, 0xffff0000, v37
	v_lshlrev_b32_e32 v124, 16, v38
	v_and_b32_e32 v125, 0xffff0000, v38
	v_lshlrev_b32_e32 v126, 16, v39
	v_and_b32_e32 v7, 0xffff0000, v39
	v_mul_f32_e32 v21, v120, v120
	v_fmac_f32_e32 v21, v121, v121
	v_fmac_f32_e32 v21, v122, v122
	v_fmac_f32_e32 v21, v123, v123
	v_fmac_f32_e32 v21, v124, v124
	v_fmac_f32_e32 v21, v125, v125
	v_fmac_f32_e32 v21, v126, v126
	v_fmac_f32_e32 v21, v7, v7
	v_lshlrev_b32_e32 v120, 16, v66
	v_and_b32_e32 v121, 0xffff0000, v66
	v_lshlrev_b32_e32 v122, 16, v67
	v_and_b32_e32 v123, 0xffff0000, v67
	v_mul_f32_e32 v113, v120, v120
; __device__ __forceinline__ u32x4 pack8f(const float* f) { u32x4 w; w.x = cvt_pk_bf16(f[0], f[1]); w.y = cvt_pk_bf16(f[2], f[3]); w.z = cvt_pk_bf16(f[4], f[5]); w.w = cvt_pk_bf16(f[6], f[7]); return w; }
; __device__ __forceinline__ void p12_lrnorm(Frame& F, const Args& A) {
;     ...
;         for (int r = 0; r < NR; ++r) { const int row = row0 + r * F.NGW; if (row < NTOK) {
;             if (row < NLAT) {
;                 float q[8]; unpack8(qraw[r], q); float ss = 0.f;
; #pragma unroll
;                 for (int j = 0; j < 8; ++j) ss += q[j] * q[j];
;                 const float rstd = rsqrtf(wave_sum(ss) * (1.0f / QLR) + EPS);
; #pragma unroll
;                 for (int j = 0; j < 8; ++j) q[j] = q[j] * rstd * gqa[8 * f_lane + j];
;                 *(u32x4*)(QL + (size_t)row * QLR + 8 * f_lane) = pack8f(q);
;             }
;             { const u32x2 raw = kraw[r]; float k[4];
;               k[0] = __uint_as_float(raw.x << 16); k[1] = __uint_as_float(raw.x & 0xffff0000u); k[2] = __uint_as_float(raw.y << 16); k[3] = __uint_as_float(raw.y & 0xffff0000u);
;               const float ss = (k[0] * k[0] + k[1] * k[1]) + (k[2] * k[2] + k[3] * k[3]);
;               const float rstd = rsqrtf(wave_sum(ss) * (1.0f / KVLR) + EPS);
	v_fmac_f32_e32 v113, v121, v121
	v_mul_f32_e32 v124, v122, v122
	v_fmac_f32_e32 v124, v123, v123
	v_add_f32_e32 v113, v113, v124
	v_lshlrev_b32_e32 v120, 16, v40
	v_and_b32_e32 v121, 0xffff0000, v40
	v_lshlrev_b32_e32 v122, 16, v41
	v_and_b32_e32 v123, 0xffff0000, v41
	v_lshlrev_b32_e32 v124, 16, v42
	v_and_b32_e32 v125, 0xffff0000, v42
	v_lshlrev_b32_e32 v126, 16, v43
	v_and_b32_e32 v7, 0xffff0000, v43
	v_mul_f32_e32 v22, v120, v120
	v_fmac_f32_e32 v22, v121, v121
	v_fmac_f32_e32 v22, v122, v122
	v_fmac_f32_e32 v22, v123, v123
	v_fmac_f32_e32 v22, v124, v124
	v_fmac_f32_e32 v22, v125, v125
	v_fmac_f32_e32 v22, v126, v126
	v_fmac_f32_e32 v22, v7, v7
	v_lshlrev_b32_e32 v120, 16, v68
	v_and_b32_e32 v121, 0xffff0000, v68
	v_lshlrev_b32_e32 v122, 16, v69
	v_and_b32_e32 v123, 0xffff0000, v69
	v_mul_f32_e32 v114, v120, v120
	v_fmac_f32_e32 v114, v121, v121
	v_mul_f32_e32 v124, v122, v122
	v_fmac_f32_e32 v124, v123, v123
	v_add_f32_e32 v114, v114, v124
	v_lshlrev_b32_e32 v120, 16, v44
	v_and_b32_e32 v121, 0xffff0000, v44
	v_lshlrev_b32_e32 v122, 16, v45
	v_and_b32_e32 v123, 0xffff0000, v45
	v_lshlrev_b32_e32 v124, 16, v46
	v_and_b32_e32 v125, 0xffff0000, v46
	v_lshlrev_b32_e32 v126, 16, v47
	v_and_b32_e32 v7, 0xffff0000, v47
	v_mul_f32_e32 v23, v120, v120
	v_fmac_f32_e32 v23, v121, v121
	v_fmac_f32_e32 v23, v122, v122
	v_fmac_f32_e32 v23, v123, v123
	v_fmac_f32_e32 v23, v124, v124
	v_fmac_f32_e32 v23, v125, v125
	v_fmac_f32_e32 v23, v126, v126
	v_fmac_f32_e32 v23, v7, v7
	v_lshlrev_b32_e32 v120, 16, v70
	v_and_b32_e32 v121, 0xffff0000, v70
	v_lshlrev_b32_e32 v122, 16, v71
	v_and_b32_e32 v123, 0xffff0000, v71
	v_mul_f32_e32 v115, v120, v120
	v_fmac_f32_e32 v115, v121, v121
	v_mul_f32_e32 v124, v122, v122
	v_fmac_f32_e32 v124, v123, v123
	v_add_f32_e32 v115, v115, v124
	v_lshlrev_b32_e32 v120, 16, v48
	v_and_b32_e32 v121, 0xffff0000, v48
	v_lshlrev_b32_e32 v122, 16, v49
	v_and_b32_e32 v123, 0xffff0000, v49
	v_lshlrev_b32_e32 v124, 16, v50
	v_and_b32_e32 v125, 0xffff0000, v50
	v_lshlrev_b32_e32 v126, 16, v51
	v_and_b32_e32 v7, 0xffff0000, v51
	v_mul_f32_e32 v24, v120, v120
	v_fmac_f32_e32 v24, v121, v121
	v_fmac_f32_e32 v24, v122, v122
	v_fmac_f32_e32 v24, v123, v123
	v_fmac_f32_e32 v24, v124, v124
	v_fmac_f32_e32 v24, v125, v125
	v_fmac_f32_e32 v24, v126, v126
	v_fmac_f32_e32 v24, v7, v7
	v_lshlrev_b32_e32 v120, 16, v72
	v_and_b32_e32 v121, 0xffff0000, v72
	v_lshlrev_b32_e32 v122, 16, v73
	v_and_b32_e32 v123, 0xffff0000, v73
	v_mul_f32_e32 v116, v120, v120
	v_fmac_f32_e32 v116, v121, v121
	v_mul_f32_e32 v124, v122, v122
	v_fmac_f32_e32 v124, v123, v123
	v_add_f32_e32 v116, v116, v124
	v_lshlrev_b32_e32 v120, 16, v52
	v_and_b32_e32 v121, 0xffff0000, v52
	v_lshlrev_b32_e32 v122, 16, v53
	v_and_b32_e32 v123, 0xffff0000, v53
	v_lshlrev_b32_e32 v124, 16, v54
	v_and_b32_e32 v125, 0xffff0000, v54
	v_lshlrev_b32_e32 v126, 16, v55
	v_and_b32_e32 v7, 0xffff0000, v55
	v_mul_f32_e32 v25, v120, v120
	v_fmac_f32_e32 v25, v121, v121
	v_fmac_f32_e32 v25, v122, v122
	v_fmac_f32_e32 v25, v123, v123
	v_fmac_f32_e32 v25, v124, v124
	v_fmac_f32_e32 v25, v125, v125
	v_fmac_f32_e32 v25, v126, v126
	v_fmac_f32_e32 v25, v7, v7
	v_lshlrev_b32_e32 v120, 16, v74
	v_and_b32_e32 v121, 0xffff0000, v74
	v_lshlrev_b32_e32 v122, 16, v75
	v_and_b32_e32 v123, 0xffff0000, v75
	v_mul_f32_e32 v117, v120, v120
	v_fmac_f32_e32 v117, v121, v121
	v_mul_f32_e32 v124, v122, v122
	v_fmac_f32_e32 v124, v123, v123
	v_add_f32_e32 v117, v117, v124
	v_lshlrev_b32_e32 v120, 16, v56
	v_and_b32_e32 v121, 0xffff0000, v56
	v_lshlrev_b32_e32 v122, 16, v57
	v_and_b32_e32 v123, 0xffff0000, v57
	v_lshlrev_b32_e32 v124, 16, v58
	v_and_b32_e32 v125, 0xffff0000, v58
	v_lshlrev_b32_e32 v126, 16, v59
	v_and_b32_e32 v7, 0xffff0000, v59
	v_mul_f32_e32 v26, v120, v120
	v_fmac_f32_e32 v26, v121, v121
	v_fmac_f32_e32 v26, v122, v122
	v_fmac_f32_e32 v26, v123, v123
	v_fmac_f32_e32 v26, v124, v124
	v_fmac_f32_e32 v26, v125, v125
	v_fmac_f32_e32 v26, v126, v126
	v_fmac_f32_e32 v26, v7, v7
	v_lshlrev_b32_e32 v120, 16, v76
	v_and_b32_e32 v121, 0xffff0000, v76
	v_lshlrev_b32_e32 v122, 16, v77
	v_and_b32_e32 v123, 0xffff0000, v77
	v_mul_f32_e32 v118, v120, v120
	v_fmac_f32_e32 v118, v121, v121
	v_mul_f32_e32 v124, v122, v122
	v_fmac_f32_e32 v124, v123, v123
	v_add_f32_e32 v118, v118, v124
	v_lshlrev_b32_e32 v120, 16, v60
	v_and_b32_e32 v121, 0xffff0000, v60
	v_lshlrev_b32_e32 v122, 16, v61
	v_and_b32_e32 v123, 0xffff0000, v61
	v_lshlrev_b32_e32 v124, 16, v62
	v_and_b32_e32 v125, 0xffff0000, v62
	v_lshlrev_b32_e32 v126, 16, v63
	v_and_b32_e32 v7, 0xffff0000, v63
	v_mul_f32_e32 v27, v120, v120
	v_fmac_f32_e32 v27, v121, v121
	v_fmac_f32_e32 v27, v122, v122
	v_fmac_f32_e32 v27, v123, v123
	v_fmac_f32_e32 v27, v124, v124
	v_fmac_f32_e32 v27, v125, v125
	v_fmac_f32_e32 v27, v126, v126
	v_fmac_f32_e32 v27, v7, v7
	v_lshlrev_b32_e32 v120, 16, v78
	v_and_b32_e32 v121, 0xffff0000, v78
	v_lshlrev_b32_e32 v122, 16, v79
	v_and_b32_e32 v123, 0xffff0000, v79
	v_mul_f32_e32 v119, v120, v120
	v_fmac_f32_e32 v119, v121, v121
	v_mul_f32_e32 v124, v122, v122
	v_fmac_f32_e32 v124, v123, v123
	v_add_f32_e32 v119, v119, v124
	v_add_f32_dpp v20, v20, v20 row_shr:1 row_mask:0xf bank_mask:0xf bound_ctrl:0
	v_add_f32_dpp v21, v21, v21 row_shr:1 row_mask:0xf bank_mask:0xf bound_ctrl:0
	v_add_f32_dpp v22, v22, v22 row_shr:1 row_mask:0xf bank_mask:0xf bound_ctrl:0
	v_add_f32_dpp v23, v23, v23 row_shr:1 row_mask:0xf bank_mask:0xf bound_ctrl:0
	v_add_f32_dpp v24, v24, v24 row_shr:1 row_mask:0xf bank_mask:0xf bound_ctrl:0
	v_add_f32_dpp v25, v25, v25 row_shr:1 row_mask:0xf bank_mask:0xf bound_ctrl:0
	v_add_f32_dpp v26, v26, v26 row_shr:1 row_mask:0xf bank_mask:0xf bound_ctrl:0
; __device__ __forceinline__ u32x4 pack8f(const float* f) { u32x4 w; w.x = cvt_pk_bf16(f[0], f[1]); w.y = cvt_pk_bf16(f[2], f[3]); w.z = cvt_pk_bf16(f[4], f[5]); w.w = cvt_pk_bf16(f[6], f[7]); return w; }
; __device__ __forceinline__ float wave_sum(float v) {
; #pragma unroll
;     for (int o = 1; o < 64; o <<= 1) v += __shfl_xor(v, o);
;     return v;
; }
; __device__ __forceinline__ void p12_lrnorm(Frame& F, const Args& A) {
;     ...
;         for (int r = 0; r < NR; ++r) { const int row = row0 + r * F.NGW; if (row < NTOK) {
;             if (row < NLAT) {
;                 float q[8]; unpack8(qraw[r], q); float ss = 0.f;
; #pragma unroll
;                 for (int j = 0; j < 8; ++j) ss += q[j] * q[j];
;                 const float rstd = rsqrtf(wave_sum(ss) * (1.0f / QLR) + EPS);
; #pragma unroll
;                 for (int j = 0; j < 8; ++j) q[j] = q[j] * rstd * gqa[8 * f_lane + j];
;                 *(u32x4*)(QL + (size_t)row * QLR + 8 * f_lane) = pack8f(q);
;             }
;             { const u32x2 raw = kraw[r]; float k[4];
;               k[0] = __uint_as_float(raw.x << 16); k[1] = __uint_as_float(raw.x & 0xffff0000u); k[2] = __uint_as_float(raw.y << 16); k[3] = __uint_as_float(raw.y & 0xffff0000u);
;               const float ss = (k[0] * k[0] + k[1] * k[1]) + (k[2] * k[2] + k[3] * k[3]);
;               const float rstd = rsqrtf(wave_sum(ss) * (1.0f / KVLR) + EPS);
	v_add_f32_dpp v27, v27, v27 row_shr:1 row_mask:0xf bank_mask:0xf bound_ctrl:0
	v_add_f32_dpp v112, v112, v112 row_shr:1 row_mask:0xf bank_mask:0xf bound_ctrl:0
	v_add_f32_dpp v113, v113, v113 row_shr:1 row_mask:0xf bank_mask:0xf bound_ctrl:0
	v_add_f32_dpp v114, v114, v114 row_shr:1 row_mask:0xf bank_mask:0xf bound_ctrl:0
	v_add_f32_dpp v115, v115, v115 row_shr:1 row_mask:0xf bank_mask:0xf bound_ctrl:0
	v_add_f32_dpp v116, v116, v116 row_shr:1 row_mask:0xf bank_mask:0xf bound_ctrl:0
	v_add_f32_dpp v117, v117, v117 row_shr:1 row_mask:0xf bank_mask:0xf bound_ctrl:0
	v_add_f32_dpp v118, v118, v118 row_shr:1 row_mask:0xf bank_mask:0xf bound_ctrl:0
	v_add_f32_dpp v119, v119, v119 row_shr:1 row_mask:0xf bank_mask:0xf bound_ctrl:0
	v_add_f32_dpp v20, v20, v20 row_shr:2 row_mask:0xf bank_mask:0xf bound_ctrl:0
	v_add_f32_dpp v21, v21, v21 row_shr:2 row_mask:0xf bank_mask:0xf bound_ctrl:0
	v_add_f32_dpp v22, v22, v22 row_shr:2 row_mask:0xf bank_mask:0xf bound_ctrl:0
	v_add_f32_dpp v23, v23, v23 row_shr:2 row_mask:0xf bank_mask:0xf bound_ctrl:0
	v_add_f32_dpp v24, v24, v24 row_shr:2 row_mask:0xf bank_mask:0xf bound_ctrl:0
	v_add_f32_dpp v25, v25, v25 row_shr:2 row_mask:0xf bank_mask:0xf bound_ctrl:0
	v_add_f32_dpp v26, v26, v26 row_shr:2 row_mask:0xf bank_mask:0xf bound_ctrl:0
	v_add_f32_dpp v27, v27, v27 row_shr:2 row_mask:0xf bank_mask:0xf bound_ctrl:0
	v_add_f32_dpp v112, v112, v112 row_shr:2 row_mask:0xf bank_mask:0xf bound_ctrl:0
	v_add_f32_dpp v113, v113, v113 row_shr:2 row_mask:0xf bank_mask:0xf bound_ctrl:0
	v_add_f32_dpp v114, v114, v114 row_shr:2 row_mask:0xf bank_mask:0xf bound_ctrl:0
	v_add_f32_dpp v115, v115, v115 row_shr:2 row_mask:0xf bank_mask:0xf bound_ctrl:0
	v_add_f32_dpp v116, v116, v116 row_shr:2 row_mask:0xf bank_mask:0xf bound_ctrl:0
	v_add_f32_dpp v117, v117, v117 row_shr:2 row_mask:0xf bank_mask:0xf bound_ctrl:0
	v_add_f32_dpp v118, v118, v118 row_shr:2 row_mask:0xf bank_mask:0xf bound_ctrl:0
	v_add_f32_dpp v119, v119, v119 row_shr:2 row_mask:0xf bank_mask:0xf bound_ctrl:0
	v_add_f32_dpp v20, v20, v20 row_shr:4 row_mask:0xf bank_mask:0xf bound_ctrl:0
	v_add_f32_dpp v21, v21, v21 row_shr:4 row_mask:0xf bank_mask:0xf bound_ctrl:0
	v_add_f32_dpp v22, v22, v22 row_shr:4 row_mask:0xf bank_mask:0xf bound_ctrl:0
	v_add_f32_dpp v23, v23, v23 row_shr:4 row_mask:0xf bank_mask:0xf bound_ctrl:0
	v_add_f32_dpp v24, v24, v24 row_shr:4 row_mask:0xf bank_mask:0xf bound_ctrl:0
	v_add_f32_dpp v25, v25, v25 row_shr:4 row_mask:0xf bank_mask:0xf bound_ctrl:0
	v_add_f32_dpp v26, v26, v26 row_shr:4 row_mask:0xf bank_mask:0xf bound_ctrl:0
	v_add_f32_dpp v27, v27, v27 row_shr:4 row_mask:0xf bank_mask:0xf bound_ctrl:0
	v_add_f32_dpp v112, v112, v112 row_shr:4 row_mask:0xf bank_mask:0xf bound_ctrl:0
	v_add_f32_dpp v113, v113, v113 row_shr:4 row_mask:0xf bank_mask:0xf bound_ctrl:0
	v_add_f32_dpp v114, v114, v114 row_shr:4 row_mask:0xf bank_mask:0xf bound_ctrl:0
	v_add_f32_dpp v115, v115, v115 row_shr:4 row_mask:0xf bank_mask:0xf bound_ctrl:0
	v_add_f32_dpp v116, v116, v116 row_shr:4 row_mask:0xf bank_mask:0xf bound_ctrl:0
	v_add_f32_dpp v117, v117, v117 row_shr:4 row_mask:0xf bank_mask:0xf bound_ctrl:0
	v_add_f32_dpp v118, v118, v118 row_shr:4 row_mask:0xf bank_mask:0xf bound_ctrl:0
	v_add_f32_dpp v119, v119, v119 row_shr:4 row_mask:0xf bank_mask:0xf bound_ctrl:0
	v_add_f32_dpp v20, v20, v20 row_shr:8 row_mask:0xf bank_mask:0xf bound_ctrl:0
	v_add_f32_dpp v21, v21, v21 row_shr:8 row_mask:0xf bank_mask:0xf bound_ctrl:0
	v_add_f32_dpp v22, v22, v22 row_shr:8 row_mask:0xf bank_mask:0xf bound_ctrl:0
	v_add_f32_dpp v23, v23, v23 row_shr:8 row_mask:0xf bank_mask:0xf bound_ctrl:0
	v_add_f32_dpp v24, v24, v24 row_shr:8 row_mask:0xf bank_mask:0xf bound_ctrl:0
	v_add_f32_dpp v25, v25, v25 row_shr:8 row_mask:0xf bank_mask:0xf bound_ctrl:0
	v_add_f32_dpp v26, v26, v26 row_shr:8 row_mask:0xf bank_mask:0xf bound_ctrl:0
	v_add_f32_dpp v27, v27, v27 row_shr:8 row_mask:0xf bank_mask:0xf bound_ctrl:0
	v_add_f32_dpp v112, v112, v112 row_shr:8 row_mask:0xf bank_mask:0xf bound_ctrl:0
	v_add_f32_dpp v113, v113, v113 row_shr:8 row_mask:0xf bank_mask:0xf bound_ctrl:0
	v_add_f32_dpp v114, v114, v114 row_shr:8 row_mask:0xf bank_mask:0xf bound_ctrl:0
	v_add_f32_dpp v115, v115, v115 row_shr:8 row_mask:0xf bank_mask:0xf bound_ctrl:0
	v_add_f32_dpp v116, v116, v116 row_shr:8 row_mask:0xf bank_mask:0xf bound_ctrl:0
	v_add_f32_dpp v117, v117, v117 row_shr:8 row_mask:0xf bank_mask:0xf bound_ctrl:0
	v_add_f32_dpp v118, v118, v118 row_shr:8 row_mask:0xf bank_mask:0xf bound_ctrl:0
	v_add_f32_dpp v119, v119, v119 row_shr:8 row_mask:0xf bank_mask:0xf bound_ctrl:0
	v_add_f32_dpp v20, v20, v20 row_bcast:15 row_mask:0xa bank_mask:0xf
	v_add_f32_dpp v21, v21, v21 row_bcast:15 row_mask:0xa bank_mask:0xf
	v_add_f32_dpp v22, v22, v22 row_bcast:15 row_mask:0xa bank_mask:0xf
	v_add_f32_dpp v23, v23, v23 row_bcast:15 row_mask:0xa bank_mask:0xf
	v_add_f32_dpp v24, v24, v24 row_bcast:15 row_mask:0xa bank_mask:0xf
	v_add_f32_dpp v25, v25, v25 row_bcast:15 row_mask:0xa bank_mask:0xf
	v_add_f32_dpp v26, v26, v26 row_bcast:15 row_mask:0xa bank_mask:0xf
	v_add_f32_dpp v27, v27, v27 row_bcast:15 row_mask:0xa bank_mask:0xf
	v_add_f32_dpp v112, v112, v112 row_bcast:15 row_mask:0xa bank_mask:0xf
	v_add_f32_dpp v113, v113, v113 row_bcast:15 row_mask:0xa bank_mask:0xf
	v_add_f32_dpp v114, v114, v114 row_bcast:15 row_mask:0xa bank_mask:0xf
	v_add_f32_dpp v115, v115, v115 row_bcast:15 row_mask:0xa bank_mask:0xf
	v_add_f32_dpp v116, v116, v116 row_bcast:15 row_mask:0xa bank_mask:0xf
	v_add_f32_dpp v117, v117, v117 row_bcast:15 row_mask:0xa bank_mask:0xf
	v_add_f32_dpp v118, v118, v118 row_bcast:15 row_mask:0xa bank_mask:0xf
; __device__ __forceinline__ unsigned cvt_pk_bf16(float lo, float hi) { unsigned r; asm volatile("v_cvt_pk_bf16_f32 %0, %1, %2" : "=v"(r) : "v"(lo), "v"(hi)); return r; }
; __device__ __forceinline__ u32x4 pack8f(const float* f) { u32x4 w; w.x = cvt_pk_bf16(f[0], f[1]); w.y = cvt_pk_bf16(f[2], f[3]); w.z = cvt_pk_bf16(f[4], f[5]); w.w = cvt_pk_bf16(f[6], f[7]); return w; }
; __device__ __forceinline__ void p12_lrnorm(Frame& F, const Args& A) {
;     ...
;         for (int r = 0; r < NR; ++r) { const int row = row0 + r * F.NGW; if (row < NTOK) {
;             if (row < NLAT) {
;                 float q[8]; unpack8(qraw[r], q); float ss = 0.f;
; #pragma unroll
;                 for (int j = 0; j < 8; ++j) ss += q[j] * q[j];
;                 const float rstd = rsqrtf(wave_sum(ss) * (1.0f / QLR) + EPS);
; #pragma unroll
;                 for (int j = 0; j < 8; ++j) q[j] = q[j] * rstd * gqa[8 * f_lane + j];
;                 *(u32x4*)(QL + (size_t)row * QLR + 8 * f_lane) = pack8f(q);
;             }
;             { const u32x2 raw = kraw[r]; float k[4];
;               k[0] = __uint_as_float(raw.x << 16); k[1] = __uint_as_float(raw.x & 0xffff0000u); k[2] = __uint_as_float(raw.y << 16); k[3] = __uint_as_float(raw.y & 0xffff0000u);
;               const float ss = (k[0] * k[0] + k[1] * k[1]) + (k[2] * k[2] + k[3] * k[3]);
;               const float rstd = rsqrtf(wave_sum(ss) * (1.0f / KVLR) + EPS);
;               const f32x4 gg = *(const f32x4*)(gkva + 4 * f_lane);
;               u32x2 w; w.x = cvt_pk_bf16(k[0] * rstd * gg.x, k[1] * rstd * gg.y); w.y = cvt_pk_bf16(k[2] * rstd * gg.z, k[3] * rstd * gg.w);
;               *(u32x2*)(CKV + (size_t)row * KVLR + 4 * f_lane) = w; }
;             if (f_lane < 4) *(u32x4*)(KPE + (size_t)row * 32 + 8 * f_lane) = praw[r]; } }
	v_add_f32_dpp v119, v119, v119 row_bcast:15 row_mask:0xa bank_mask:0xf
	v_add_f32_dpp v20, v20, v20 row_bcast:31 row_mask:0xc bank_mask:0xf
	v_add_f32_dpp v21, v21, v21 row_bcast:31 row_mask:0xc bank_mask:0xf
	v_add_f32_dpp v22, v22, v22 row_bcast:31 row_mask:0xc bank_mask:0xf
	v_add_f32_dpp v23, v23, v23 row_bcast:31 row_mask:0xc bank_mask:0xf
	v_add_f32_dpp v24, v24, v24 row_bcast:31 row_mask:0xc bank_mask:0xf
	v_add_f32_dpp v25, v25, v25 row_bcast:31 row_mask:0xc bank_mask:0xf
	v_add_f32_dpp v26, v26, v26 row_bcast:31 row_mask:0xc bank_mask:0xf
	v_add_f32_dpp v27, v27, v27 row_bcast:31 row_mask:0xc bank_mask:0xf
	v_add_f32_dpp v112, v112, v112 row_bcast:31 row_mask:0xc bank_mask:0xf
	v_add_f32_dpp v113, v113, v113 row_bcast:31 row_mask:0xc bank_mask:0xf
	v_add_f32_dpp v114, v114, v114 row_bcast:31 row_mask:0xc bank_mask:0xf
	v_add_f32_dpp v115, v115, v115 row_bcast:31 row_mask:0xc bank_mask:0xf
	v_add_f32_dpp v116, v116, v116 row_bcast:31 row_mask:0xc bank_mask:0xf
	v_add_f32_dpp v117, v117, v117 row_bcast:31 row_mask:0xc bank_mask:0xf
	v_add_f32_dpp v118, v118, v118 row_bcast:31 row_mask:0xc bank_mask:0xf
	v_add_f32_dpp v119, v119, v119 row_bcast:31 row_mask:0xc bank_mask:0xf
	v_readlane_b32 s47, v20, 63
	v_readlane_b32 s48, v21, 63
	v_readlane_b32 s49, v22, 63
	v_readlane_b32 s50, v23, 63
	v_readlane_b32 s51, v24, 63
	v_readlane_b32 s52, v25, 63
	v_readlane_b32 s53, v26, 63
	v_readlane_b32 s54, v27, 63
	v_readlane_b32 s55, v112, 63
	v_readlane_b32 s56, v113, 63
	v_readlane_b32 s57, v114, 63
	v_readlane_b32 s58, v115, 63
	v_readlane_b32 s59, v116, 63
	v_readlane_b32 s60, v117, 63
	v_readlane_b32 s61, v118, 63
	v_readlane_b32 s62, v119, 63
	v_mov_b32_e32 v5, 0x3b000000
	v_mov_b32_e32 v6, 0x358637bd
	v_mov_b32_e32 v0, 0x3b800000
	s_cmp_lt_u32 s34, 0x8800
	s_cbranch_scc0 .Llr_skip0
	s_cmp_lt_u32 s34, 0x8000
	s_cbranch_scc0 .Llr_noq0
	v_fma_f32 v1, s47, v5, v6
	v_rsq_f32_e32 v1, v1
	v_lshlrev_b32_e32 v120, 16, v32
	v_and_b32_e32 v121, 0xffff0000, v32
	v_lshlrev_b32_e32 v122, 16, v33
	v_and_b32_e32 v123, 0xffff0000, v33
	v_lshlrev_b32_e32 v124, 16, v34
	v_and_b32_e32 v125, 0xffff0000, v34
	v_lshlrev_b32_e32 v126, 16, v35
	v_and_b32_e32 v7, 0xffff0000, v35
	v_mul_f32_e32 v120, v120, v1
	v_mul_f32_e32 v121, v121, v1
	v_mul_f32_e32 v122, v122, v1
	v_mul_f32_e32 v123, v123, v1
	v_mul_f32_e32 v124, v124, v1
	v_mul_f32_e32 v125, v125, v1
	v_mul_f32_e32 v126, v126, v1
	v_mul_f32_e32 v7, v7, v1
	v_mul_f32_e32 v120, v120, v8
	v_mul_f32_e32 v121, v121, v9
	v_mul_f32_e32 v122, v122, v10
	v_mul_f32_e32 v123, v123, v11
	v_mul_f32_e32 v124, v124, v12
	v_mul_f32_e32 v125, v125, v13
	v_mul_f32_e32 v126, v126, v14
	v_mul_f32_e32 v7, v7, v15
	v_cvt_pk_bf16_f32 v32, v120, v121
	v_cvt_pk_bf16_f32 v33, v122, v123
	v_cvt_pk_bf16_f32 v34, v124, v125
	v_cvt_pk_bf16_f32 v35, v126, v7
	s_lshl_b32 s13, s22, 10
	s_add_u32 s30, s6, s13
	s_addc_u32 s31, s7, 0
	global_store_dwordx4 v3, v[32:35], s[30:31]
.Llr_noq0:
	v_fma_f32 v1, s55, v0, v6
	v_rsq_f32_e32 v1, v1
	v_lshlrev_b32_e32 v120, 16, v64
	v_and_b32_e32 v121, 0xffff0000, v64
	v_lshlrev_b32_e32 v122, 16, v65
	v_and_b32_e32 v123, 0xffff0000, v65
	v_mul_f32_e32 v120, v120, v1
	v_mul_f32_e32 v121, v121, v1
	v_mul_f32_e32 v122, v122, v1
	v_mul_f32_e32 v123, v123, v1
	v_mul_f32_e32 v120, v120, v16
	v_mul_f32_e32 v121, v121, v17
	v_mul_f32_e32 v122, v122, v18
	v_mul_f32_e32 v123, v123, v19
	v_cvt_pk_bf16_f32 v64, v120, v121
	v_cvt_pk_bf16_f32 v65, v122, v123
	s_lshl_b32 s13, s22, 9
	s_add_u32 s30, s8, s13
	s_addc_u32 s31, s9, 0
	global_store_dwordx2 v4, v[64:65], s[30:31]
	s_lshl_b32 s13, s22, 6
	s_add_u32 s30, s10, s13
	s_addc_u32 s31, s11, 0
	s_mov_b64 exec, 15
	global_store_dwordx4 v3, v[80:83], s[30:31]
	s_mov_b64 exec, -1
.Llr_skip0:
	s_cmp_lt_u32 s35, 0x8800
	s_cbranch_scc0 .Llr_skip1
	s_cmp_lt_u32 s35, 0x8000
	s_cbranch_scc0 .Llr_noq1
	v_fma_f32 v1, s48, v5, v6
	v_rsq_f32_e32 v1, v1
	v_lshlrev_b32_e32 v120, 16, v36
	v_and_b32_e32 v121, 0xffff0000, v36
	v_lshlrev_b32_e32 v122, 16, v37
	v_and_b32_e32 v123, 0xffff0000, v37
	v_lshlrev_b32_e32 v124, 16, v38
	v_and_b32_e32 v125, 0xffff0000, v38
	v_lshlrev_b32_e32 v126, 16, v39
	v_and_b32_e32 v7, 0xffff0000, v39
	v_mul_f32_e32 v120, v120, v1
	v_mul_f32_e32 v121, v121, v1
	v_mul_f32_e32 v122, v122, v1
	v_mul_f32_e32 v123, v123, v1
	v_mul_f32_e32 v124, v124, v1
	v_mul_f32_e32 v125, v125, v1
	v_mul_f32_e32 v126, v126, v1
	v_mul_f32_e32 v7, v7, v1
	v_mul_f32_e32 v120, v120, v8
	v_mul_f32_e32 v121, v121, v9
	v_mul_f32_e32 v122, v122, v10
	v_mul_f32_e32 v123, v123, v11
	v_mul_f32_e32 v124, v124, v12
	v_mul_f32_e32 v125, v125, v13
	v_mul_f32_e32 v126, v126, v14
	v_mul_f32_e32 v7, v7, v15
	v_cvt_pk_bf16_f32 v36, v120, v121
	v_cvt_pk_bf16_f32 v37, v122, v123
	v_cvt_pk_bf16_f32 v38, v124, v125
	v_cvt_pk_bf16_f32 v39, v126, v7
	s_lshl_b32 s13, s23, 10
	s_add_u32 s30, s6, s13
	s_addc_u32 s31, s7, 0
	global_store_dwordx4 v3, v[36:39], s[30:31]
.Llr_noq1:
	v_fma_f32 v1, s56, v0, v6
	v_rsq_f32_e32 v1, v1
	v_lshlrev_b32_e32 v120, 16, v66
	v_and_b32_e32 v121, 0xffff0000, v66
	v_lshlrev_b32_e32 v122, 16, v67
	v_and_b32_e32 v123, 0xffff0000, v67
	v_mul_f32_e32 v120, v120, v1
	v_mul_f32_e32 v121, v121, v1
	v_mul_f32_e32 v122, v122, v1
	v_mul_f32_e32 v123, v123, v1
	v_mul_f32_e32 v120, v120, v16
	v_mul_f32_e32 v121, v121, v17
	v_mul_f32_e32 v122, v122, v18
	v_mul_f32_e32 v123, v123, v19
	v_cvt_pk_bf16_f32 v66, v120, v121
	v_cvt_pk_bf16_f32 v67, v122, v123
	s_lshl_b32 s13, s23, 9
	s_add_u32 s30, s8, s13
	s_addc_u32 s31, s9, 0
	global_store_dwordx2 v4, v[66:67], s[30:31]
	s_lshl_b32 s13, s23, 6
	s_add_u32 s30, s10, s13
	s_addc_u32 s31, s11, 0
	s_mov_b64 exec, 15
	global_store_dwordx4 v3, v[84:87], s[30:31]
	s_mov_b64 exec, -1
; __device__ __forceinline__ unsigned cvt_pk_bf16(float lo, float hi) { unsigned r; asm volatile("v_cvt_pk_bf16_f32 %0, %1, %2" : "=v"(r) : "v"(lo), "v"(hi)); return r; }
; __device__ __forceinline__ u32x4 pack8f(const float* f) { u32x4 w; w.x = cvt_pk_bf16(f[0], f[1]); w.y = cvt_pk_bf16(f[2], f[3]); w.z = cvt_pk_bf16(f[4], f[5]); w.w = cvt_pk_bf16(f[6], f[7]); return w; }
; __device__ __forceinline__ void p12_lrnorm(Frame& F, const Args& A) {
;     ...
;         for (int r = 0; r < NR; ++r) { const int row = row0 + r * F.NGW; if (row < NTOK) {
;             if (row < NLAT) {
;                 float q[8]; unpack8(qraw[r], q); float ss = 0.f;
; #pragma unroll
;                 for (int j = 0; j < 8; ++j) ss += q[j] * q[j];
;                 const float rstd = rsqrtf(wave_sum(ss) * (1.0f / QLR) + EPS);
; #pragma unroll
;                 for (int j = 0; j < 8; ++j) q[j] = q[j] * rstd * gqa[8 * f_lane + j];
;                 *(u32x4*)(QL + (size_t)row * QLR + 8 * f_lane) = pack8f(q);
;             }
;             { const u32x2 raw = kraw[r]; float k[4];
;               k[0] = __uint_as_float(raw.x << 16); k[1] = __uint_as_float(raw.x & 0xffff0000u); k[2] = __uint_as_float(raw.y << 16); k[3] = __uint_as_float(raw.y & 0xffff0000u);
;               const float ss = (k[0] * k[0] + k[1] * k[1]) + (k[2] * k[2] + k[3] * k[3]);
;               const float rstd = rsqrtf(wave_sum(ss) * (1.0f / KVLR) + EPS);
;               const f32x4 gg = *(const f32x4*)(gkva + 4 * f_lane);
;               u32x2 w; w.x = cvt_pk_bf16(k[0] * rstd * gg.x, k[1] * rstd * gg.y); w.y = cvt_pk_bf16(k[2] * rstd * gg.z, k[3] * rstd * gg.w);
;               *(u32x2*)(CKV + (size_t)row * KVLR + 4 * f_lane) = w; }
;             if (f_lane < 4) *(u32x4*)(KPE + (size_t)row * 32 + 8 * f_lane) = praw[r]; } }
.Llr_skip1:
	s_cmp_lt_u32 s36, 0x8800
	s_cbranch_scc0 .Llr_skip2
	s_cmp_lt_u32 s36, 0x8000
	s_cbranch_scc0 .Llr_noq2
	v_fma_f32 v1, s49, v5, v6
	v_rsq_f32_e32 v1, v1
	v_lshlrev_b32_e32 v120, 16, v40
	v_and_b32_e32 v121, 0xffff0000, v40
	v_lshlrev_b32_e32 v122, 16, v41
	v_and_b32_e32 v123, 0xffff0000, v41
	v_lshlrev_b32_e32 v124, 16, v42
	v_and_b32_e32 v125, 0xffff0000, v42
	v_lshlrev_b32_e32 v126, 16, v43
	v_and_b32_e32 v7, 0xffff0000, v43
	v_mul_f32_e32 v120, v120, v1
	v_mul_f32_e32 v121, v121, v1
	v_mul_f32_e32 v122, v122, v1
	v_mul_f32_e32 v123, v123, v1
	v_mul_f32_e32 v124, v124, v1
	v_mul_f32_e32 v125, v125, v1
	v_mul_f32_e32 v126, v126, v1
	v_mul_f32_e32 v7, v7, v1
	v_mul_f32_e32 v120, v120, v8
	v_mul_f32_e32 v121, v121, v9
	v_mul_f32_e32 v122, v122, v10
	v_mul_f32_e32 v123, v123, v11
	v_mul_f32_e32 v124, v124, v12
	v_mul_f32_e32 v125, v125, v13
	v_mul_f32_e32 v126, v126, v14
	v_mul_f32_e32 v7, v7, v15
	v_cvt_pk_bf16_f32 v40, v120, v121
	v_cvt_pk_bf16_f32 v41, v122, v123
	v_cvt_pk_bf16_f32 v42, v124, v125
	v_cvt_pk_bf16_f32 v43, v126, v7
	s_lshl_b32 s13, s24, 10
	s_add_u32 s30, s6, s13
	s_addc_u32 s31, s7, 0
	global_store_dwordx4 v3, v[40:43], s[30:31]
.Llr_noq2:
	v_fma_f32 v1, s57, v0, v6
	v_rsq_f32_e32 v1, v1
	v_lshlrev_b32_e32 v120, 16, v68
	v_and_b32_e32 v121, 0xffff0000, v68
	v_lshlrev_b32_e32 v122, 16, v69
	v_and_b32_e32 v123, 0xffff0000, v69
	v_mul_f32_e32 v120, v120, v1
	v_mul_f32_e32 v121, v121, v1
	v_mul_f32_e32 v122, v122, v1
	v_mul_f32_e32 v123, v123, v1
	v_mul_f32_e32 v120, v120, v16
	v_mul_f32_e32 v121, v121, v17
	v_mul_f32_e32 v122, v122, v18
	v_mul_f32_e32 v123, v123, v19
	v_cvt_pk_bf16_f32 v68, v120, v121
	v_cvt_pk_bf16_f32 v69, v122, v123
	s_lshl_b32 s13, s24, 9
	s_add_u32 s30, s8, s13
	s_addc_u32 s31, s9, 0
	global_store_dwordx2 v4, v[68:69], s[30:31]
	s_lshl_b32 s13, s24, 6
	s_add_u32 s30, s10, s13
	s_addc_u32 s31, s11, 0
	s_mov_b64 exec, 15
	global_store_dwordx4 v3, v[88:91], s[30:31]
	s_mov_b64 exec, -1
.Llr_skip2:
	s_cmp_lt_u32 s37, 0x8800
	s_cbranch_scc0 .Llr_skip3
	s_cmp_lt_u32 s37, 0x8000
	s_cbranch_scc0 .Llr_noq3
	v_fma_f32 v1, s50, v5, v6
	v_rsq_f32_e32 v1, v1
	v_lshlrev_b32_e32 v120, 16, v44
	v_and_b32_e32 v121, 0xffff0000, v44
	v_lshlrev_b32_e32 v122, 16, v45
	v_and_b32_e32 v123, 0xffff0000, v45
	v_lshlrev_b32_e32 v124, 16, v46
	v_and_b32_e32 v125, 0xffff0000, v46
	v_lshlrev_b32_e32 v126, 16, v47
	v_and_b32_e32 v7, 0xffff0000, v47
	v_mul_f32_e32 v120, v120, v1
	v_mul_f32_e32 v121, v121, v1
	v_mul_f32_e32 v122, v122, v1
	v_mul_f32_e32 v123, v123, v1
	v_mul_f32_e32 v124, v124, v1
	v_mul_f32_e32 v125, v125, v1
	v_mul_f32_e32 v126, v126, v1
	v_mul_f32_e32 v7, v7, v1
	v_mul_f32_e32 v120, v120, v8
	v_mul_f32_e32 v121, v121, v9
	v_mul_f32_e32 v122, v122, v10
	v_mul_f32_e32 v123, v123, v11
	v_mul_f32_e32 v124, v124, v12
	v_mul_f32_e32 v125, v125, v13
	v_mul_f32_e32 v126, v126, v14
	v_mul_f32_e32 v7, v7, v15
	v_cvt_pk_bf16_f32 v44, v120, v121
	v_cvt_pk_bf16_f32 v45, v122, v123
	v_cvt_pk_bf16_f32 v46, v124, v125
	v_cvt_pk_bf16_f32 v47, v126, v7
	s_lshl_b32 s13, s25, 10
	s_add_u32 s30, s6, s13
	s_addc_u32 s31, s7, 0
	global_store_dwordx4 v3, v[44:47], s[30:31]
.Llr_noq3:
	v_fma_f32 v1, s58, v0, v6
	v_rsq_f32_e32 v1, v1
	v_lshlrev_b32_e32 v120, 16, v70
	v_and_b32_e32 v121, 0xffff0000, v70
	v_lshlrev_b32_e32 v122, 16, v71
	v_and_b32_e32 v123, 0xffff0000, v71
	v_mul_f32_e32 v120, v120, v1
	v_mul_f32_e32 v121, v121, v1
	v_mul_f32_e32 v122, v122, v1
	v_mul_f32_e32 v123, v123, v1
	v_mul_f32_e32 v120, v120, v16
	v_mul_f32_e32 v121, v121, v17
	v_mul_f32_e32 v122, v122, v18
	v_mul_f32_e32 v123, v123, v19
	v_cvt_pk_bf16_f32 v70, v120, v121
	v_cvt_pk_bf16_f32 v71, v122, v123
	s_lshl_b32 s13, s25, 9
	s_add_u32 s30, s8, s13
	s_addc_u32 s31, s9, 0
	global_store_dwordx2 v4, v[70:71], s[30:31]
	s_lshl_b32 s13, s25, 6
	s_add_u32 s30, s10, s13
	s_addc_u32 s31, s11, 0
	s_mov_b64 exec, 15
	global_store_dwordx4 v3, v[92:95], s[30:31]
	s_mov_b64 exec, -1
.Llr_skip3:
	s_cmp_lt_u32 s38, 0x8800
	s_cbranch_scc0 .Llr_skip4
	s_cmp_lt_u32 s38, 0x8000
	s_cbranch_scc0 .Llr_noq4
	v_fma_f32 v1, s51, v5, v6
	v_rsq_f32_e32 v1, v1
	v_lshlrev_b32_e32 v120, 16, v48
	v_and_b32_e32 v121, 0xffff0000, v48
	v_lshlrev_b32_e32 v122, 16, v49
	v_and_b32_e32 v123, 0xffff0000, v49
	v_lshlrev_b32_e32 v124, 16, v50
	v_and_b32_e32 v125, 0xffff0000, v50
	v_lshlrev_b32_e32 v126, 16, v51
	v_and_b32_e32 v7, 0xffff0000, v51
	v_mul_f32_e32 v120, v120, v1
	v_mul_f32_e32 v121, v121, v1
	v_mul_f32_e32 v122, v122, v1
	v_mul_f32_e32 v123, v123, v1
	v_mul_f32_e32 v124, v124, v1
	v_mul_f32_e32 v125, v125, v1
	v_mul_f32_e32 v126, v126, v1
	v_mul_f32_e32 v7, v7, v1
	v_mul_f32_e32 v120, v120, v8
	v_mul_f32_e32 v121, v121, v9
	v_mul_f32_e32 v122, v122, v10
	v_mul_f32_e32 v123, v123, v11
	v_mul_f32_e32 v124, v124, v12
	v_mul_f32_e32 v125, v125, v13
	v_mul_f32_e32 v126, v126, v14
	v_mul_f32_e32 v7, v7, v15
	v_cvt_pk_bf16_f32 v48, v120, v121
	v_cvt_pk_bf16_f32 v49, v122, v123
	v_cvt_pk_bf16_f32 v50, v124, v125
	v_cvt_pk_bf16_f32 v51, v126, v7
	s_lshl_b32 s13, s26, 10
	s_add_u32 s30, s6, s13
	s_addc_u32 s31, s7, 0
	global_store_dwordx4 v3, v[48:51], s[30:31]
.Llr_noq4:
	v_fma_f32 v1, s59, v0, v6
	v_rsq_f32_e32 v1, v1
	v_lshlrev_b32_e32 v120, 16, v72
	v_and_b32_e32 v121, 0xffff0000, v72
	v_lshlrev_b32_e32 v122, 16, v73
	v_and_b32_e32 v123, 0xffff0000, v73
	v_mul_f32_e32 v120, v120, v1
	v_mul_f32_e32 v121, v121, v1
	v_mul_f32_e32 v122, v122, v1
	v_mul_f32_e32 v123, v123, v1
	v_mul_f32_e32 v120, v120, v16
	v_mul_f32_e32 v121, v121, v17
	v_mul_f32_e32 v122, v122, v18
	v_mul_f32_e32 v123, v123, v19
	v_cvt_pk_bf16_f32 v72, v120, v121
	v_cvt_pk_bf16_f32 v73, v122, v123
	s_lshl_b32 s13, s26, 9
	s_add_u32 s30, s8, s13
	s_addc_u32 s31, s9, 0
	global_store_dwordx2 v4, v[72:73], s[30:31]
	s_lshl_b32 s13, s26, 6
	s_add_u32 s30, s10, s13
	s_addc_u32 s31, s11, 0
	s_mov_b64 exec, 15
	global_store_dwordx4 v3, v[96:99], s[30:31]
	s_mov_b64 exec, -1
; __device__ __forceinline__ unsigned cvt_pk_bf16(float lo, float hi) { unsigned r; asm volatile("v_cvt_pk_bf16_f32 %0, %1, %2" : "=v"(r) : "v"(lo), "v"(hi)); return r; }
; __device__ __forceinline__ u32x4 pack8f(const float* f) { u32x4 w; w.x = cvt_pk_bf16(f[0], f[1]); w.y = cvt_pk_bf16(f[2], f[3]); w.z = cvt_pk_bf16(f[4], f[5]); w.w = cvt_pk_bf16(f[6], f[7]); return w; }
; __device__ __forceinline__ void p12_lrnorm(Frame& F, const Args& A) {
;     ...
;     for (int row0 = F.gw; row0 < NTOK; row0 += NR * F.NGW) {
;         bf16x8 qraw[NR]; u32x2 kraw[NR]; u32x4 praw[NR];
; #pragma unroll
;         for (int r = 0; r < NR; ++r) { const int row = row0 + r * F.NGW; if (row < NTOK) { const bf16* pr = PX + (size_t)row * DM;
;             if (row < NLAT) qraw[r] = *(const bf16x8*)(pr + 8 * f_lane);
;             kraw[r] = *(const u32x2*)(pr + QLR + 4 * f_lane);
;             if (f_lane < 4) praw[r] = *(const u32x4*)(pr + QLR + KVLR + 8 * f_lane); } }
; #pragma unroll
;         for (int r = 0; r < NR; ++r) { const int row = row0 + r * F.NGW; if (row < NTOK) {
;             if (row < NLAT) {
;                 float q[8]; unpack8(qraw[r], q); float ss = 0.f;
; #pragma unroll
;                 for (int j = 0; j < 8; ++j) ss += q[j] * q[j];
;                 const float rstd = rsqrtf(wave_sum(ss) * (1.0f / QLR) + EPS);
; #pragma unroll
;                 for (int j = 0; j < 8; ++j) q[j] = q[j] * rstd * gqa[8 * f_lane + j];
;                 *(u32x4*)(QL + (size_t)row * QLR + 8 * f_lane) = pack8f(q);
;             }
;             { const u32x2 raw = kraw[r]; float k[4];
;               k[0] = __uint_as_float(raw.x << 16); k[1] = __uint_as_float(raw.x & 0xffff0000u); k[2] = __uint_as_float(raw.y << 16); k[3] = __uint_as_float(raw.y & 0xffff0000u);
;               const float ss = (k[0] * k[0] + k[1] * k[1]) + (k[2] * k[2] + k[3] * k[3]);
;               const float rstd = rsqrtf(wave_sum(ss) * (1.0f / KVLR) + EPS);
;               const f32x4 gg = *(const f32x4*)(gkva + 4 * f_lane);
;               u32x2 w; w.x = cvt_pk_bf16(k[0] * rstd * gg.x, k[1] * rstd * gg.y); w.y = cvt_pk_bf16(k[2] * rstd * gg.z, k[3] * rstd * gg.w);
;               *(u32x2*)(CKV + (size_t)row * KVLR + 4 * f_lane) = w; }
;             if (f_lane < 4) *(u32x4*)(KPE + (size_t)row * 32 + 8 * f_lane) = praw[r]; } }
;     }
.Llr_skip4:
	s_cmp_lt_u32 s39, 0x8800
	s_cbranch_scc0 .Llr_skip5
	s_cmp_lt_u32 s39, 0x8000
	s_cbranch_scc0 .Llr_noq5
	v_fma_f32 v1, s52, v5, v6
	v_rsq_f32_e32 v1, v1
	v_lshlrev_b32_e32 v120, 16, v52
	v_and_b32_e32 v121, 0xffff0000, v52
	v_lshlrev_b32_e32 v122, 16, v53
	v_and_b32_e32 v123, 0xffff0000, v53
	v_lshlrev_b32_e32 v124, 16, v54
	v_and_b32_e32 v125, 0xffff0000, v54
	v_lshlrev_b32_e32 v126, 16, v55
	v_and_b32_e32 v7, 0xffff0000, v55
	v_mul_f32_e32 v120, v120, v1
	v_mul_f32_e32 v121, v121, v1
	v_mul_f32_e32 v122, v122, v1
	v_mul_f32_e32 v123, v123, v1
	v_mul_f32_e32 v124, v124, v1
	v_mul_f32_e32 v125, v125, v1
	v_mul_f32_e32 v126, v126, v1
	v_mul_f32_e32 v7, v7, v1
	v_mul_f32_e32 v120, v120, v8
	v_mul_f32_e32 v121, v121, v9
	v_mul_f32_e32 v122, v122, v10
	v_mul_f32_e32 v123, v123, v11
	v_mul_f32_e32 v124, v124, v12
	v_mul_f32_e32 v125, v125, v13
	v_mul_f32_e32 v126, v126, v14
	v_mul_f32_e32 v7, v7, v15
	v_cvt_pk_bf16_f32 v52, v120, v121
	v_cvt_pk_bf16_f32 v53, v122, v123
	v_cvt_pk_bf16_f32 v54, v124, v125
	v_cvt_pk_bf16_f32 v55, v126, v7
	s_lshl_b32 s13, s27, 10
	s_add_u32 s30, s6, s13
	s_addc_u32 s31, s7, 0
	global_store_dwordx4 v3, v[52:55], s[30:31]
.Llr_noq5:
	v_fma_f32 v1, s60, v0, v6
	v_rsq_f32_e32 v1, v1
	v_lshlrev_b32_e32 v120, 16, v74
	v_and_b32_e32 v121, 0xffff0000, v74
	v_lshlrev_b32_e32 v122, 16, v75
	v_and_b32_e32 v123, 0xffff0000, v75
	v_mul_f32_e32 v120, v120, v1
	v_mul_f32_e32 v121, v121, v1
	v_mul_f32_e32 v122, v122, v1
	v_mul_f32_e32 v123, v123, v1
	v_mul_f32_e32 v120, v120, v16
	v_mul_f32_e32 v121, v121, v17
	v_mul_f32_e32 v122, v122, v18
	v_mul_f32_e32 v123, v123, v19
	v_cvt_pk_bf16_f32 v74, v120, v121
	v_cvt_pk_bf16_f32 v75, v122, v123
	s_lshl_b32 s13, s27, 9
	s_add_u32 s30, s8, s13
	s_addc_u32 s31, s9, 0
	global_store_dwordx2 v4, v[74:75], s[30:31]
	s_lshl_b32 s13, s27, 6
	s_add_u32 s30, s10, s13
	s_addc_u32 s31, s11, 0
	s_mov_b64 exec, 15
	global_store_dwordx4 v3, v[100:103], s[30:31]
	s_mov_b64 exec, -1
.Llr_skip5:
	s_cmp_lt_u32 s40, 0x8800
	s_cbranch_scc0 .Llr_skip6
	s_cmp_lt_u32 s40, 0x8000
	s_cbranch_scc0 .Llr_noq6
	v_fma_f32 v1, s53, v5, v6
	v_rsq_f32_e32 v1, v1
	v_lshlrev_b32_e32 v120, 16, v56
	v_and_b32_e32 v121, 0xffff0000, v56
	v_lshlrev_b32_e32 v122, 16, v57
	v_and_b32_e32 v123, 0xffff0000, v57
	v_lshlrev_b32_e32 v124, 16, v58
	v_and_b32_e32 v125, 0xffff0000, v58
	v_lshlrev_b32_e32 v126, 16, v59
	v_and_b32_e32 v7, 0xffff0000, v59
	v_mul_f32_e32 v120, v120, v1
	v_mul_f32_e32 v121, v121, v1
	v_mul_f32_e32 v122, v122, v1
	v_mul_f32_e32 v123, v123, v1
	v_mul_f32_e32 v124, v124, v1
	v_mul_f32_e32 v125, v125, v1
	v_mul_f32_e32 v126, v126, v1
	v_mul_f32_e32 v7, v7, v1
	v_mul_f32_e32 v120, v120, v8
	v_mul_f32_e32 v121, v121, v9
	v_mul_f32_e32 v122, v122, v10
	v_mul_f32_e32 v123, v123, v11
	v_mul_f32_e32 v124, v124, v12
	v_mul_f32_e32 v125, v125, v13
	v_mul_f32_e32 v126, v126, v14
	v_mul_f32_e32 v7, v7, v15
	v_cvt_pk_bf16_f32 v56, v120, v121
	v_cvt_pk_bf16_f32 v57, v122, v123
	v_cvt_pk_bf16_f32 v58, v124, v125
	v_cvt_pk_bf16_f32 v59, v126, v7
	s_lshl_b32 s13, s28, 10
	s_add_u32 s30, s6, s13
	s_addc_u32 s31, s7, 0
	global_store_dwordx4 v3, v[56:59], s[30:31]
.Llr_noq6:
	v_fma_f32 v1, s61, v0, v6
	v_rsq_f32_e32 v1, v1
	v_lshlrev_b32_e32 v120, 16, v76
	v_and_b32_e32 v121, 0xffff0000, v76
	v_lshlrev_b32_e32 v122, 16, v77
	v_and_b32_e32 v123, 0xffff0000, v77
	v_mul_f32_e32 v120, v120, v1
	v_mul_f32_e32 v121, v121, v1
	v_mul_f32_e32 v122, v122, v1
	v_mul_f32_e32 v123, v123, v1
	v_mul_f32_e32 v120, v120, v16
	v_mul_f32_e32 v121, v121, v17
	v_mul_f32_e32 v122, v122, v18
	v_mul_f32_e32 v123, v123, v19
	v_cvt_pk_bf16_f32 v76, v120, v121
	v_cvt_pk_bf16_f32 v77, v122, v123
	s_lshl_b32 s13, s28, 9
	s_add_u32 s30, s8, s13
	s_addc_u32 s31, s9, 0
	global_store_dwordx2 v4, v[76:77], s[30:31]
	s_lshl_b32 s13, s28, 6
	s_add_u32 s30, s10, s13
	s_addc_u32 s31, s11, 0
	s_mov_b64 exec, 15
	global_store_dwordx4 v3, v[104:107], s[30:31]
	s_mov_b64 exec, -1
.Llr_skip6:
	s_cmp_lt_u32 s41, 0x8800
	s_cbranch_scc0 .Llr_skip7
	s_cmp_lt_u32 s41, 0x8000
	s_cbranch_scc0 .Llr_noq7
	v_fma_f32 v1, s54, v5, v6
	v_rsq_f32_e32 v1, v1
	v_lshlrev_b32_e32 v120, 16, v60
	v_and_b32_e32 v121, 0xffff0000, v60
	v_lshlrev_b32_e32 v122, 16, v61
	v_and_b32_e32 v123, 0xffff0000, v61
	v_lshlrev_b32_e32 v124, 16, v62
	v_and_b32_e32 v125, 0xffff0000, v62
	v_lshlrev_b32_e32 v126, 16, v63
	v_and_b32_e32 v7, 0xffff0000, v63
	v_mul_f32_e32 v120, v120, v1
	v_mul_f32_e32 v121, v121, v1
	v_mul_f32_e32 v122, v122, v1
	v_mul_f32_e32 v123, v123, v1
	v_mul_f32_e32 v124, v124, v1
	v_mul_f32_e32 v125, v125, v1
	v_mul_f32_e32 v126, v126, v1
	v_mul_f32_e32 v7, v7, v1
	v_mul_f32_e32 v120, v120, v8
	v_mul_f32_e32 v121, v121, v9
	v_mul_f32_e32 v122, v122, v10
	v_mul_f32_e32 v123, v123, v11
	v_mul_f32_e32 v124, v124, v12
	v_mul_f32_e32 v125, v125, v13
	v_mul_f32_e32 v126, v126, v14
	v_mul_f32_e32 v7, v7, v15
	v_cvt_pk_bf16_f32 v60, v120, v121
	v_cvt_pk_bf16_f32 v61, v122, v123
	v_cvt_pk_bf16_f32 v62, v124, v125
	v_cvt_pk_bf16_f32 v63, v126, v7
	s_lshl_b32 s13, s29, 10
	s_add_u32 s30, s6, s13
	s_addc_u32 s31, s7, 0
	global_store_dwordx4 v3, v[60:63], s[30:31]
.Llr_noq7:
	v_fma_f32 v1, s62, v0, v6
	v_rsq_f32_e32 v1, v1
	v_lshlrev_b32_e32 v120, 16, v78
	v_and_b32_e32 v121, 0xffff0000, v78
	v_lshlrev_b32_e32 v122, 16, v79
	v_and_b32_e32 v123, 0xffff0000, v79
	v_mul_f32_e32 v120, v120, v1
	v_mul_f32_e32 v121, v121, v1
	v_mul_f32_e32 v122, v122, v1
	v_mul_f32_e32 v123, v123, v1
	v_mul_f32_e32 v120, v120, v16
	v_mul_f32_e32 v121, v121, v17
	v_mul_f32_e32 v122, v122, v18
	v_mul_f32_e32 v123, v123, v19
	v_cvt_pk_bf16_f32 v78, v120, v121
	v_cvt_pk_bf16_f32 v79, v122, v123
	s_lshl_b32 s13, s29, 9
	s_add_u32 s30, s8, s13
	s_addc_u32 s31, s9, 0
	global_store_dwordx2 v4, v[78:79], s[30:31]
	s_lshl_b32 s13, s29, 6
	s_add_u32 s30, s10, s13
	s_addc_u32 s31, s11, 0
	s_mov_b64 exec, 15
	global_store_dwordx4 v3, v[108:111], s[30:31]
	s_mov_b64 exec, -1
.Llr_skip7:
	s_add_i32 s12, s12, 8
	s_mul_i32 s13, s12, s76
	s_add_i32 s13, s13, s46
	s_cmp_lt_i32 s13, 0x8800
	s_cbranch_scc1 .Llr_step
